# MLA static units: next-unit prefetch also across the (batch, head) change (all three unit transitions of a workgroup now enter through the load-free prologue)
# speedup vs baseline: 1.0071x; 1.0071x over previous
;     ...
;     const int q0 = NMETA + 256 * qi;
;     const int qw0 = q0 + 32 * wid;
;     const int myq = qw0 + ln;
;     const int nkt = (q0 + 255) / 64 + 1;
;     bf16x8 qf[KS];
; #pragma unroll
;     for (int ks = 0; ks < KS; ++ks) {
;         if (ks < 4) qf[ks] = *(const bf16x8*)(qa + (size_t)myq * ldqa + ks * 16 + h * 8);
;         else qf[ks] = *(const bf16x8*)(qb + (size_t)myq * ldqb + (ks - 4) * 16 + h * 8);
;     }
;     ...
;     auto gload = [&](int j) {
; #pragma unroll
;         for (int r = 0; r < NK2; ++r) {
;             const int c = tid + NT * r;
;             if (c < 64 * KCH) { const int row = c / KCH, ch = c - row * KCH; kr[r] = *(const u32x4*)(kbase + (size_t)(64 * j + row) * ldk + ch * 8); }
;         }
;         { const int row = tid >> 3, ch = tid & 7; vr = *(const u32x4*)(vt + (size_t)row * LP + 64 * j + ch * 8); }
;         if (FOX) { if (tid < 64) br = bias[64 * j + tid]; }
.LBB0_737:
	s_and_b64 s[10:11], s[8:9], exec
	s_cselect_b32 s12, s59, s58
	s_cbranch_scc0 .Lmp_pro
	s_and_b64 vcc, exec, s[46:47]
	s_cbranch_vccnz .Lmp_pro
	v_add3_u32 v159, v137, s12, 16
	v_add_u32_e32 v2, v159, v208
	v_ashrrev_i32_e32 v3, 31, v2
	v_lshlrev_b64 v[4:5], 10, v[2:3]
	v_lshlrev_b64 v[2:3], 11, v[2:3]
	v_lshl_add_u64 v[2:3], v[160:161], 0, v[2:3]
	global_load_dwordx4 v[66:69], v[2:3], off
	global_load_dwordx4 v[70:73], v[2:3], off offset:32
	global_load_dwordx4 v[74:77], v[2:3], off offset:64
	global_load_dwordx4 v[78:81], v[2:3], off offset:96
	v_lshl_add_u64 v[2:3], v[170:171], 0, v[4:5]
	global_load_dwordx4 v[82:85], v[2:3], off
	global_load_dwordx4 v[86:89], v[2:3], off offset:32
	s_add_i32 s13, s12, 0x10f
	s_and_b32 s2, s13, 0x1f00
	s_and_saveexec_b64 s[10:11], s[4:5]
	s_cbranch_execz .LBB0_739
	v_add_u32_e32 v1, s2, v184
	v_mad_i64_i32 v[2:3], s[14:15], v1, s70, v[164:165]
	global_load_dwordx4 v[90:93], v[2:3], off

;     ...
;     auto gload = [&](int j) {
; #pragma unroll
;         for (int r = 0; r < NK2; ++r) {
;             const int c = tid + NT * r;
;             if (c < 64 * KCH) { const int row = c / KCH, ch = c - row * KCH; kr[r] = *(const u32x4*)(kbase + (size_t)(64 * j + row) * ldk + ch * 8); }
;         }
;         { const int row = tid >> 3, ch = tid & 7; vr = *(const u32x4*)(vt + (size_t)row * LP + 64 * j + ch * 8); }
;         if (FOX) { if (tid < 64) br = bias[64 * j + tid]; }
; DI void phase3(const Params& p, unsigned char* smem, int tid, int cidx) {
;     ...
;         for (int r = 0; r < 2; ++r) {
;             const int bh = (r * 4 + s4) * 8 + xcd, b = bh >> 4, hd = bh & 15;
;             const size_t t0 = (size_t)b * L;
;             for (int half = 0; half < 2; ++half) {
;                 const int qi = half == 0 ? 15 - j8 : j8;
;                 bf16_t* qn = (bf16_t*)(ws + OFF_QN) + t0 * 1024 + hd * 64;
;                 attn_unit<96, false>(qn, 1024, (const bf16_t*)(ws + OFF_QPE) + t0 * 512 + hd * 32, 512,
;                                      (const bf16_t*)(ob + OUT_KM) + t0 * 1536 + hd * 96, 1536,
;                                      (const bf16_t*)(ws + OFF_VMT) + (size_t)(b * NH + hd) * 64 * LP, nullptr, qn, 1024, qi, lds, tid);
.Lmp_lastG_r:
	s_and_b64 vcc, exec, s[46:47]
	s_cbranch_vccnz .LBB0_754
	s_or_b32 s96, s3, 32
	s_lshr_b32 s97, s96, 4
	s_mul_i32 s100, s97, 0x1010
	s_mov_b32 s101, 0
	s_mul_i32 s98, s97, 0xc0c000
	s_mul_hi_u32 s99, s100, 0xc00
	s_add_u32 s98, s50, s98
	s_addc_u32 s99, s51, s99
	s_add_i32 s97, s59, 0x10f
	s_and_b32 s97, s97, 0x1f00
	s_and_saveexec_b64 vcc, s[4:5]
	s_cbranch_execz .Lmp_rk1
	v_add_u32_e32 v1, s97, v184
	v_lshl_add_u64 v[34:35], v[138:139], 1, s[98:99]
	v_mad_i64_i32 v[34:35], s[14:15], v1, s70, v[34:35]
	global_load_dwordx4 v[90:93], v[34:35], off
.Lmp_rk1:
	s_or_b64 exec, exec, vcc
	s_and_saveexec_b64 vcc, s[6:7]
	s_cbranch_execz .Lmp_rk2
	v_add_u32_e32 v1, s97, v189
	v_lshl_add_u64 v[34:35], v[144:145], 1, s[98:99]
	v_mad_i64_i32 v[34:35], s[14:15], v1, s70, v[34:35]
	global_load_dwordx4 v[94:97], v[34:35], off
.Lmp_rk2:
	s_or_b64 exec, exec, vcc
	s_or_b32 s98, s96, s16
	s_mul_i32 s98, s98, 0x41000
	s_mov_b32 s99, 0
	v_lshl_add_u64 v[34:35], s[98:99], 1, v[146:147]
	s_lshl_b32 s98, s97, 1
	v_lshl_add_u64 v[34:35], v[34:35], 0, s[98:99]
	global_load_dwordx4 v[98:101], v[34:35], off
	s_branch .LBB0_754
.Lmp_last_r:
	s_and_b64 vcc, exec, s[46:47]
	s_cbranch_vccnz .LBB0_747
	s_lshl_b64 s[98:99], s[100:101], 11
	s_add_u32 s98, s17, s98
	s_addc_u32 s99, s33, s99
	v_lshlrev_b32_e32 v44, 1, v152
	v_mov_b32_e32 v45, 0
	v_lshl_add_u64 v[44:45], s[98:99], 0, v[44:45]
	v_add3_u32 v40, v137, s59, 16
	v_add_u32_e32 v40, v40, v208
	v_ashrrev_i32_e32 v41, 31, v40
	v_lshlrev_b64 v[42:43], 10, v[40:41]
	v_lshlrev_b64 v[40:41], 11, v[40:41]
	v_lshl_add_u64 v[40:41], v[44:45], 0, v[40:41]
	global_load_dwordx4 v[66:69], v[40:41], off
	global_load_dwordx4 v[70:73], v[40:41], off offset:32
	global_load_dwordx4 v[74:77], v[40:41], off offset:64
	global_load_dwordx4 v[78:81], v[40:41], off offset:96
	s_lshl_b64 s[98:99], s[100:101], 10
	v_lshl_add_u64 v[44:45], v[148:149], 0, s[98:99]
	v_lshl_add_u64 v[42:43], v[44:45], 0, v[42:43]
	global_load_dwordx4 v[82:85], v[42:43], off
	global_load_dwordx4 v[86:89], v[42:43], off offset:32
	s_branch .LBB0_747
